# P2 short conv: conv-weight register copies moved behind the first iteration's input-load issue (no separate wait on the weight loads), so weight and input load latencies overlap
# baseline (speedup 1.0000x reference)
.LBB0_270:
	v_or_b32_e32 v124, s8, v164
	v_med3_i32 v26, v124, 0, v197
	v_max_i32_e32 v27, -4, v124
	v_ashrrev_i32_e32 v125, 31, v124
	v_mov_b64_e32 v[24:25], s[72:73]
	v_or_b32_e32 v30, s38, v26
	v_add_u32_e32 v34, 4, v27
	v_lshl_add_u64 v[26:27], s[38:39], 0, v[124:125]
	v_add_u32_e32 v28, -1, v124
	v_or_b32_e32 v128, 1, v124
	v_mad_u64_u32 v[24:25], s[10:11], v26, s28, v[24:25]
	v_or_b32_e32 v126, 2, v124
	v_or_b32_e32 v122, 3, v124
	v_med3_i32 v29, v28, 0, v197
	v_med3_i32 v31, v128, 0, v197
	v_min_u32_e32 v40, 0xfff, v34
	v_mad_i32_i24 v25, v27, s28, v25
	v_med3_i32 v32, v126, 0, v197
	v_med3_i32 v33, v122, 0, v197
	v_cmp_gt_u32_e32 vcc, s46, v28
	v_or_b32_e32 v35, s38, v29
	v_mad_u64_u32 v[28:29], s[10:11], v30, s28, v[70:71]
	v_or_b32_e32 v36, s38, v31
	v_lshlrev_b64 v[30:31], 11, v[26:27]
	v_or_b32_e32 v26, s38, v40
	v_lshl_add_u64 v[24:25], v[24:25], 0, v[178:179]
	v_cndmask_b32_e64 v64, 0, 1.0, vcc
	v_or_b32_e32 v37, s38, v32
	v_or_b32_e32 v38, s38, v33
	v_lshl_add_u64 v[146:147], v[72:73], 0, v[30:31]
	v_mad_u64_u32 v[30:31], s[10:11], v26, s28, v[70:71]
	v_add_co_u32_e32 v26, vcc, s46, v24
	v_mad_u64_u32 v[32:33], s[10:11], v35, s28, v[70:71]
	v_mad_i32_i24 v29, s39, v187, v29
	v_mad_u64_u32 v[34:35], s[10:11], v36, s28, v[70:71]
	v_mad_u64_u32 v[36:37], s[10:11], v37, s28, v[70:71]
	v_mad_u64_u32 v[38:39], s[10:11], v38, s28, v[70:71]
	v_addc_co_u32_e32 v27, vcc, 0, v25, vcc
	global_load_dwordx4 v[130:133], v[28:29], off offset:2560
	v_mad_i32_i24 v33, s39, v187, v33
	v_mad_i32_i24 v35, s39, v187, v35
	v_mad_i32_i24 v37, s39, v187, v37
	v_mad_i32_i24 v39, s39, v187, v39
	global_load_dwordx4 v[134:137], v[28:29], off offset:3584
	global_load_dwordx4 v[138:141], v[34:35], off offset:2560
	global_load_dwordx4 v[142:145], v[32:33], off offset:2560
	global_load_dwordx4 v[148:151], v[34:35], off offset:3584
	global_load_dwordx4 v[152:155], v[32:33], off offset:3584
	global_load_dwordx4 v[156:159], v[36:37], off offset:3584
	global_load_dwordx4 v[160:163], v[36:37], off offset:2560
	global_load_dwordx4 v[48:51], v[38:39], off offset:3584
	global_load_dwordx4 v[166:169], v[24:25], off offset:1536
	v_add_co_u32_e32 v28, vcc, s54, v24
	v_mad_i32_i24 v31, s39, v187, v31
	s_nop 0
	v_addc_co_u32_e32 v29, vcc, 0, v25, vcc
	v_add_co_u32_e32 v36, vcc, s55, v24
	s_mov_b32 s8, 4
	s_nop 0
	v_addc_co_u32_e32 v37, vcc, 0, v25, vcc
	v_add_co_u32_e32 v174, vcc, s64, v24
	s_waitcnt vmcnt(8)
	v_lshlrev_b32_e32 v200, 16, v135
	v_addc_co_u32_e32 v175, vcc, 0, v25, vcc
	v_add_co_u32_e32 v180, vcc, s65, v24
	s_waitcnt vmcnt(7)
	v_lshlrev_b32_e32 v211, 16, v138
	v_addc_co_u32_e32 v181, vcc, 0, v25, vcc
	global_load_dwordx4 v[52:55], v[38:39], off offset:2560
	global_load_dwordx4 v[32:35], v[30:31], off offset:3584
	global_load_dwordx4 v[170:173], v[26:27], off offset:1536
	global_load_dwordx4 v[56:59], v[28:29], off offset:-4096
	global_load_dwordx4 v[60:63], v[28:29], off
	global_load_dwordx4 v[40:43], v[28:29], off offset:2560
	global_load_dwordx4 v[44:47], v[36:37], off offset:2560
	s_nop 0
	global_load_dwordx4 v[24:27], v[174:175], off offset:1024
	global_load_dwordx4 v[36:39], v[30:31], off offset:2560
	s_nop 0
	global_load_dwordx4 v[28:31], v[180:181], off offset:1024
	s_cmp_eq_u64 s[0:1], 0
	s_cbranch_scc1 .Lcw_skip
	v_mov_b32_e32 v74, v2
	v_mov_b32_e32 v75, v6
	v_mov_b32_e32 v76, v3
	v_mov_b32_e32 v77, v7
	v_mov_b32_e32 v78, v0
	v_mov_b32_e32 v79, v4
	v_mov_b32_e32 v80, v1
	v_mov_b32_e32 v81, v5
	v_mov_b32_e32 v82, v10
	v_mov_b32_e32 v83, v14
	v_mov_b32_e32 v84, v11
	v_mov_b32_e32 v85, v15
	v_mov_b32_e32 v86, v8
	v_mov_b32_e32 v87, v12
	v_mov_b32_e32 v88, v9
	v_mov_b32_e32 v89, v13
	v_mov_b32_e32 v90, v2
	v_mov_b32_e32 v91, v18
	v_mov_b32_e32 v92, v3
	v_mov_b32_e32 v93, v19
	v_mov_b32_e32 v94, v0
	v_mov_b32_e32 v95, v16
	v_mov_b32_e32 v96, v1
	v_mov_b32_e32 v97, v17
	v_mov_b32_e32 v98, v10
	v_mov_b32_e32 v99, v22
	v_mov_b32_e32 v100, v11
	v_mov_b32_e32 v101, v23
	v_mov_b32_e32 v102, v8
	v_mov_b32_e32 v103, v20
	v_mov_b32_e32 v104, v9
	v_mov_b32_e32 v105, v21
	v_mov_b32_e32 v106, v18
	v_mov_b32_e32 v107, v6
	v_mov_b32_e32 v108, v19
	v_mov_b32_e32 v109, v7
	v_mov_b32_e32 v110, v16
	v_mov_b32_e32 v111, v4
	v_mov_b32_e32 v112, v17
	v_mov_b32_e32 v113, v5
	v_mov_b32_e32 v114, v22
	v_mov_b32_e32 v115, v14
	v_mov_b32_e32 v116, v23
	v_mov_b32_e32 v117, v15
	v_mov_b32_e32 v118, v20
	v_mov_b32_e32 v119, v12
	v_mov_b32_e32 v120, v21
	v_mov_b32_e32 v121, v13
.Lcw_skip:
	s_waitcnt vmcnt(16)
	v_lshlrev_b32_e32 v210, 16, v142
	s_waitcnt vmcnt(15)
	v_lshlrev_b32_e32 v213, 16, v148
	s_waitcnt vmcnt(14)
	v_lshlrev_b32_e32 v212, 16, v152
	v_and_b32_e32 v215, 0xffff0000, v138
	v_and_b32_e32 v214, 0xffff0000, v142
	v_and_b32_e32 v217, 0xffff0000, v148
	v_and_b32_e32 v216, 0xffff0000, v152
	v_lshlrev_b32_e32 v219, 16, v139
	v_lshlrev_b32_e32 v218, 16, v143
	v_lshlrev_b32_e32 v221, 16, v149
	v_lshlrev_b32_e32 v220, 16, v153
	v_and_b32_e32 v139, 0xffff0000, v139
	v_and_b32_e32 v138, 0xffff0000, v143
	v_and_b32_e32 v143, 0xffff0000, v149
	v_and_b32_e32 v142, 0xffff0000, v153
	v_lshlrev_b32_e32 v149, 16, v140
	v_lshlrev_b32_e32 v148, 16, v144
	v_lshlrev_b32_e32 v153, 16, v150
	v_lshlrev_b32_e32 v152, 16, v154
	v_and_b32_e32 v223, 0xffff0000, v140
	v_and_b32_e32 v222, 0xffff0000, v144
	v_and_b32_e32 v225, 0xffff0000, v150
	v_and_b32_e32 v224, 0xffff0000, v154
	v_lshlrev_b32_e32 v227, 16, v141
	v_lshlrev_b32_e32 v226, 16, v145
	v_lshlrev_b32_e32 v229, 16, v151
	v_lshlrev_b32_e32 v228, 16, v155
	v_and_b32_e32 v141, 0xffff0000, v141
	v_and_b32_e32 v140, 0xffff0000, v145
	v_and_b32_e32 v145, 0xffff0000, v151
	v_and_b32_e32 v144, 0xffff0000, v155
	v_and_b32_e32 v202, 0xffff0000, v135
	s_waitcnt vmcnt(13)
	v_lshlrev_b32_e32 v193, 16, v156
	v_and_b32_e32 v135, 0xffff0000, v156
	v_lshlrev_b32_e32 v201, 16, v157
	v_and_b32_e32 v203, 0xffff0000, v157
	v_pk_mul_f32 v[150:151], v[210:211], v[212:213]
	v_pk_mul_f32 v[154:155], v[214:215], v[216:217]
	v_pk_mul_f32 v[156:157], v[218:219], v[220:221]
	v_pk_mul_f32 v[138:139], v[138:139], v[142:143]
	v_pk_mul_f32 v[142:143], v[148:149], v[152:153]
	v_pk_mul_f32 v[148:149], v[222:223], v[224:225]
	v_pk_mul_f32 v[210:211], v[226:227], v[228:229]
	v_pk_mul_f32 v[140:141], v[140:141], v[144:145]
	v_lshlrev_b32_e32 v180, 16, v131
	v_and_b32_e32 v182, 0xffff0000, v131
	v_lshlrev_b32_e32 v188, 16, v133
	v_and_b32_e32 v190, 0xffff0000, v133
	v_lshlrev_b32_e32 v206, 16, v137
	v_and_b32_e32 v208, 0xffff0000, v137
	s_waitcnt vmcnt(12)
	v_lshlrev_b32_e32 v175, 16, v160
	v_and_b32_e32 v131, 0xffff0000, v160
	v_lshlrev_b32_e32 v181, 16, v161
	v_and_b32_e32 v183, 0xffff0000, v161
	v_lshlrev_b32_e32 v185, 16, v162
	v_lshlrev_b32_e32 v205, 16, v158
	v_and_b32_e32 v133, 0xffff0000, v162
	v_and_b32_e32 v137, 0xffff0000, v158
	v_lshlrev_b32_e32 v189, 16, v163
	v_lshlrev_b32_e32 v207, 16, v159
	v_and_b32_e32 v191, 0xffff0000, v163
	v_and_b32_e32 v209, 0xffff0000, v159
	v_pk_mul_f32 v[162:163], v[64:65], v[150:151]
	v_pk_mul_f32 v[160:161], v[64:65], v[154:155]
	v_pk_mul_f32 v[158:159], v[64:65], v[156:157]
	v_pk_mul_f32 v[156:157], v[64:65], v[138:139]
	v_pk_mul_f32 v[154:155], v[64:65], v[142:143]
	v_pk_mul_f32 v[152:153], v[64:65], v[148:149]
	v_pk_mul_f32 v[150:151], v[64:65], v[210:211]
	v_pk_mul_f32 v[148:149], v[64:65], v[140:141]
	v_lshlrev_b32_e32 v174, 16, v130
	v_and_b32_e32 v130, 0xffff0000, v130
	s_waitcnt vmcnt(7)
	v_lshlrev_b32_e32 v230, 16, v170
	v_and_b32_e32 v232, 0xffff0000, v170
	v_mul_f32_e32 v64, 0xbfb8aa3b, v230
	v_lshlrev_b32_e32 v234, 16, v171
	v_mul_f32_e32 v67, 0xbfb8aa3b, v232
	v_exp_f32_e32 v64, v64
	v_lshlrev_b32_e32 v192, 16, v134
	v_and_b32_e32 v134, 0xffff0000, v134
	v_lshlrev_b32_e32 v231, 16, v166
	v_and_b32_e32 v233, 0xffff0000, v166
	v_and_b32_e32 v166, 0xffff0000, v171
	v_mul_f32_e32 v123, 0xbfb8aa3b, v234
	v_exp_f32_e32 v67, v67
	v_lshlrev_b32_e32 v236, 16, v172
	v_pk_mul_f32 v[144:145], v[192:193], v[174:175]
	v_pk_mul_f32 v[130:131], v[134:135], v[130:131]
	v_pk_mul_f32 v[134:135], v[200:201], v[180:181]
	v_pk_mul_f32 v[170:171], v[202:203], v[182:183]
	v_pk_mul_f32 v[180:181], v[208:209], v[190:191]
	v_mul_f32_e32 v125, 0xbfb8aa3b, v166
	v_exp_f32_e32 v123, v123
	v_lshlrev_b32_e32 v184, 16, v132
	v_lshlrev_b32_e32 v204, 16, v136
	v_and_b32_e32 v238, 0xffff0000, v172
	v_mul_f32_e32 v127, 0xbfb8aa3b, v236
	v_pk_mul_f32 v[144:145], v[68:69], v[144:145]
	v_pk_mul_f32 v[142:143], v[68:69], v[130:131]
	v_pk_mul_f32 v[138:139], v[68:69], v[170:171]
	v_pk_mul_f32 v[130:131], v[68:69], v[180:181]
	v_pk_mul_f32 v[170:171], v[86:87], v[162:163]
	v_pk_mul_f32 v[190:191], v[76:77], v[148:149]
	v_exp_f32_e32 v125, v125
	v_and_b32_e32 v132, 0xffff0000, v132
	v_and_b32_e32 v136, 0xffff0000, v136
	v_lshlrev_b32_e32 v237, 16, v168
	v_and_b32_e32 v239, 0xffff0000, v168
	v_lshlrev_b32_e32 v240, 16, v173
	v_and_b32_e32 v168, 0xffff0000, v173
	v_pk_mul_f32 v[172:173], v[204:205], v[184:185]
	v_mul_f32_e32 v129, 0xbfb8aa3b, v238
	v_exp_f32_e32 v127, v127
	v_pk_mul_f32 v[192:193], v[86:87], v[144:145]
	v_fma_f32 v144, v20, v144, v170
	v_fma_f32 v170, v19, v130, v190
	v_add_f32_e32 v64, 1.0, v64
	v_pk_mul_f32 v[132:133], v[136:137], v[132:133]
	v_pk_mul_f32 v[174:175], v[206:207], v[188:189]
	v_mul_f32_e32 v165, 0xbfb8aa3b, v240
	v_pk_mul_f32 v[136:137], v[68:69], v[172:173]
	v_pk_mul_f32 v[172:173], v[88:89], v[160:161]
	v_exp_f32_e32 v129, v129
	v_add_f32_e32 v191, v170, v191
	v_add_f32_e32 v67, 1.0, v67
	v_rcp_f32_e32 v170, v64
	v_mul_f32_e32 v186, 0xbfb8aa3b, v168
	v_pk_mul_f32 v[140:141], v[68:69], v[134:135]
	v_pk_mul_f32 v[134:135], v[68:69], v[132:133]
	v_pk_mul_f32 v[132:133], v[68:69], v[174:175]
	v_pk_mul_f32 v[174:175], v[82:83], v[158:159]
	v_exp_f32_e32 v148, v165
	v_pk_mul_f32 v[200:201], v[88:89], v[142:143]
	v_fma_f32 v142, v21, v142, v172
	v_add_f32_e32 v123, 1.0, v123
	v_rcp_f32_e32 v172, v67
	v_pk_mul_f32 v[180:181], v[84:85], v[156:157]
	v_pk_mul_f32 v[188:189], v[74:75], v[150:151]
	v_exp_f32_e32 v150, v186
	v_pk_mul_f32 v[202:203], v[82:83], v[140:141]
	v_fma_f32 v140, v22, v140, v174
	v_add_f32_e32 v125, 1.0, v125
	v_rcp_f32_e32 v174, v123
	v_pk_mul_f32 v[182:183], v[78:79], v[154:155]
	v_pk_mul_f32 v[204:205], v[84:85], v[138:139]
	v_fma_f32 v138, v23, v138, v180
	v_add_f32_e32 v171, v144, v171
	v_add_f32_e32 v127, 1.0, v127
	v_rcp_f32_e32 v180, v125
	v_pk_mul_f32 v[184:185], v[80:81], v[152:153]
	v_pk_mul_f32 v[206:207], v[78:79], v[136:137]
	v_pk_mul_f32 v[210:211], v[74:75], v[132:133]
	v_fma_f32 v136, v16, v136, v182
	v_fma_f32 v132, v18, v132, v188
	v_add_f32_e32 v173, v142, v173
	v_add_f32_e32 v129, 1.0, v129
	v_rcp_f32_e32 v182, v127
	v_pk_mul_f32 v[170:171], v[170:171], v[230:231]
	v_lshlrev_b32_e32 v235, 16, v167
	v_pk_mul_f32 v[208:209], v[80:81], v[134:135]
	v_fma_f32 v134, v17, v134, v184
	v_add_f32_e32 v175, v140, v175
	v_add_f32_e32 v189, v132, v189
	v_add_f32_e32 v132, 1.0, v148
	v_rcp_f32_e32 v184, v129
	v_pk_mul_f32 v[172:173], v[172:173], v[232:233]
	v_mul_f32_e32 v64, v171, v171
	v_and_b32_e32 v167, 0xffff0000, v167
	v_add_f32_e32 v181, v138, v181
	v_add_f32_e32 v185, v134, v185
	v_add_f32_e32 v134, 1.0, v150
	v_rcp_f32_e32 v188, v132
	v_pk_mul_f32 v[174:175], v[174:175], v[234:235]
	v_fmac_f32_e32 v64, v173, v173
	v_add_f32_e32 v183, v136, v183
	v_rcp_f32_e32 v190, v134
	v_pk_mul_f32 v[166:167], v[180:181], v[166:167]
	v_fmac_f32_e32 v64, v175, v175
	v_pk_mul_f32 v[180:181], v[182:183], v[236:237]
	v_fmac_f32_e32 v64, v167, v167
	v_lshlrev_b32_e32 v241, 16, v169
	v_pk_mul_f32 v[182:183], v[184:185], v[238:239]
	v_fmac_f32_e32 v64, v181, v181
	v_and_b32_e32 v169, 0xffff0000, v169
	v_pk_mul_f32 v[184:185], v[188:189], v[240:241]
	v_fmac_f32_e32 v64, v183, v183
	v_pk_mul_f32 v[168:169], v[190:191], v[168:169]
	v_fmac_f32_e32 v64, v185, v185
	v_fmac_f32_e32 v64, v169, v169
	v_fma_f32 v152, v20, v163, v192
	v_fma_f32 v154, v21, v161, v200
	v_fma_f32 v156, v22, v159, v202
	v_fma_f32 v158, v23, v157, v204
	v_add_f32_dpp v64, v64, v64 quad_perm:[1,0,3,2] row_mask:0xf bank_mask:0xf
	v_fma_f32 v160, v16, v155, v206
	v_fma_f32 v162, v17, v153, v208
	v_fma_f32 v165, v18, v151, v210
	v_add_f32_e32 v193, v152, v193
	v_add_f32_dpp v64, v64, v64 quad_perm:[2,3,0,1] row_mask:0xf bank_mask:0xf
	v_add_f32_e32 v201, v154, v201
	v_add_f32_e32 v203, v156, v203
	v_add_f32_e32 v205, v158, v205
	v_add_f32_e32 v207, v160, v207
	v_add_f32_dpp v64, v64, v64 row_half_mirror row_mask:0xf bank_mask:0xf
	v_add_f32_e32 v209, v162, v209
	v_add_f32_e32 v211, v165, v211
	v_add_f32_dpp v64, v64, v64 row_mirror row_mask:0xf bank_mask:0xf
	v_mov_b32_e32 v67, v64
	s_nop 1
	v_permlane16_swap_b32_e32 v64, v67
	v_add_f32_e32 v64, v64, v67
	v_mov_b32_e32 v67, v64
	s_nop 1
	v_permlane32_swap_b32_e32 v64, v67
	v_add_f32_e32 v64, v64, v67
	v_fmamk_f32 v64, v64, 0x3b000000, v196
	v_mul_f32_e32 v67, 0x4b800000, v64
	v_cmp_gt_f32_e32 vcc, s35, v64
	s_nop 1
	v_cndmask_b32_e32 v64, v64, v67, vcc
	v_rsq_f32_e32 v64, v64
	s_nop 0
	v_mul_f32_e32 v67, 0x45800000, v64
	v_cndmask_b32_e32 v64, v64, v67, vcc
	v_mul_f32_e32 v67, v171, v64
	v_mul_f32_e32 v123, v173, v64
	v_mul_f32_e32 v125, v175, v64
	v_mul_f32_e32 v127, v167, v64
	v_mul_f32_e32 v129, v181, v64
	v_mul_f32_e32 v132, v183, v64
	v_mul_f32_e32 v134, v185, v64
	v_mul_f32_e32 v64, v169, v64
	v_mul_f32_e32 v67, v170, v67
	v_mul_f32_e32 v123, v172, v123
	v_mul_f32_e32 v125, v174, v125
	v_mul_f32_e32 v127, v166, v127
	v_mul_f32_e32 v129, v180, v129
	v_mul_f32_e32 v132, v182, v132
	v_mul_f32_e32 v134, v184, v134
	v_mul_f32_e32 v64, v168, v64
	v_cvt_pk_bf16_f32 v166, v67, v123
	v_cvt_pk_bf16_f32 v167, v125, v127
	v_cvt_pk_bf16_f32 v168, v129, v132
	v_cvt_pk_bf16_f32 v169, v134, v64
	global_store_dwordx4 v[146:147], v[166:169], off offset:1024
	v_pk_mul_f32 v[146:147], v[76:77], v[130:131]
	s_waitcnt vmcnt(6)
	v_and_b32_e32 v166, 0xffff0000, v60
	v_fma_f32 v64, v19, v149, v146
	v_lshlrev_b32_e32 v146, 16, v60
	v_mul_f32_e32 v60, 0xbfb8aa3b, v166
	v_exp_f32_e32 v60, v60
	v_mul_f32_e32 v67, 0xbfb8aa3b, v146
	v_exp_f32_e32 v67, v67
	v_add_f32_e32 v169, v64, v147
	v_add_f32_e32 v60, 1.0, v60
	v_rcp_f32_e32 v200, v60
	v_lshlrev_b32_e32 v60, 16, v61
	v_add_f32_e32 v64, 1.0, v67
	v_lshlrev_b32_e32 v147, 16, v56
	v_and_b32_e32 v167, 0xffff0000, v56
	v_mul_f32_e32 v56, 0xbfb8aa3b, v60
	v_rcp_f32_e32 v192, v64
	v_exp_f32_e32 v64, v56
	v_and_b32_e32 v56, 0xffff0000, v61
	v_mul_f32_e32 v61, 0xbfb8aa3b, v56
	v_exp_f32_e32 v67, v61
	v_add_f32_e32 v64, 1.0, v64
	v_rcp_f32_e32 v202, v64
	v_lshlrev_b32_e32 v170, 16, v62
	v_add_f32_e32 v64, 1.0, v67
	v_rcp_f32_e32 v204, v64
	v_mul_f32_e32 v64, 0xbfb8aa3b, v170
	v_exp_f32_e32 v64, v64
	v_lshlrev_b32_e32 v61, 16, v57
	v_and_b32_e32 v57, 0xffff0000, v57
	v_pk_mul_f32 v[172:173], v[204:205], v[56:57]
	v_add_f32_e32 v56, 1.0, v64
	v_rcp_f32_e32 v206, v56
	v_and_b32_e32 v56, 0xffff0000, v62
	v_mul_f32_e32 v57, 0xbfb8aa3b, v56
	v_exp_f32_e32 v62, v57
	v_lshlrev_b32_e32 v171, 16, v58
	v_and_b32_e32 v57, 0xffff0000, v58
	v_pk_mul_f32 v[146:147], v[192:193], v[146:147]
	v_add_f32_e32 v58, 1.0, v62
	v_lshlrev_b32_e32 v62, 16, v63
	v_rcp_f32_e32 v208, v58
	v_mul_f32_e32 v58, 0xbfb8aa3b, v62
	v_exp_f32_e32 v64, v58
	v_and_b32_e32 v58, 0xffff0000, v63
	v_mul_f32_e32 v63, 0xbfb8aa3b, v58
	v_exp_f32_e32 v63, v63
	v_pk_mul_f32 v[174:175], v[208:209], v[56:57]
	v_add_f32_e32 v56, 1.0, v64
	v_rcp_f32_e32 v210, v56
	v_add_f32_e32 v56, 1.0, v63
	v_pk_mul_f32 v[166:167], v[200:201], v[166:167]
	v_rcp_f32_e32 v168, v56
	v_mul_f32_e32 v56, v147, v147
	v_pk_mul_f32 v[60:61], v[202:203], v[60:61]
	v_fmac_f32_e32 v56, v167, v167
	v_fmac_f32_e32 v56, v61, v61
	v_pk_mul_f32 v[170:171], v[206:207], v[170:171]
	v_fmac_f32_e32 v56, v173, v173
	v_lshlrev_b32_e32 v63, 16, v59
	v_fmac_f32_e32 v56, v171, v171
	v_pk_mul_f32 v[62:63], v[210:211], v[62:63]
	v_and_b32_e32 v59, 0xffff0000, v59
	v_fmac_f32_e32 v56, v175, v175
	v_pk_mul_f32 v[168:169], v[168:169], v[58:59]
	v_fmac_f32_e32 v56, v63, v63
	v_fmac_f32_e32 v56, v169, v169
	v_ashrrev_i32_e32 v129, 31, v128
	s_nop 0
	v_add_f32_dpp v56, v56, v56 quad_perm:[1,0,3,2] row_mask:0xf bank_mask:0xf
	s_nop 1
	v_add_f32_dpp v56, v56, v56 quad_perm:[2,3,0,1] row_mask:0xf bank_mask:0xf
	s_nop 1
	v_add_f32_dpp v56, v56, v56 row_half_mirror row_mask:0xf bank_mask:0xf
	s_nop 1
	v_add_f32_dpp v56, v56, v56 row_mirror row_mask:0xf bank_mask:0xf
	v_mov_b32_e32 v57, v56
	s_nop 1
	v_permlane16_swap_b32_e32 v56, v57
	v_add_f32_e32 v56, v56, v57
	v_mov_b32_e32 v57, v56
	s_nop 1
	v_permlane32_swap_b32_e32 v56, v57
	v_add_f32_e32 v56, v56, v57
	v_fmamk_f32 v56, v56, 0x3b000000, v196
	v_mul_f32_e32 v57, 0x4b800000, v56
	v_cmp_gt_f32_e32 vcc, s35, v56
	s_nop 1
	v_cndmask_b32_e32 v56, v56, v57, vcc
	v_rsq_f32_e32 v56, v56
	s_nop 0
	v_mul_f32_e32 v57, 0x45800000, v56
	v_cndmask_b32_e32 v59, v56, v57, vcc
	v_mul_f32_e32 v56, v147, v59
	v_mul_f32_e32 v57, v167, v59
	v_mul_f32_e32 v56, v146, v56
	v_mul_f32_e32 v57, v166, v57
	v_cvt_pk_bf16_f32 v56, v56, v57
	v_mul_f32_e32 v57, v61, v59
	v_mul_f32_e32 v58, v173, v59
	v_mul_f32_e32 v57, v60, v57
	v_mul_f32_e32 v58, v172, v58
	v_cvt_pk_bf16_f32 v57, v57, v58
	v_mul_f32_e32 v58, v171, v59
	v_mul_f32_e32 v60, v175, v59
	v_mul_f32_e32 v58, v170, v58
	v_mul_f32_e32 v60, v174, v60
	v_cvt_pk_bf16_f32 v58, v58, v60
	v_mul_f32_e32 v60, v63, v59
	v_mul_f32_e32 v59, v169, v59
	v_mul_f32_e32 v60, v62, v60
	v_mul_f32_e32 v59, v168, v59
	v_cvt_pk_bf16_f32 v59, v60, v59
	v_lshl_add_u64 v[60:61], s[38:39], 0, v[128:129]
	v_lshlrev_b64 v[60:61], 11, v[60:61]
	v_lshl_add_u64 v[60:61], v[72:73], 0, v[60:61]
	global_store_dwordx4 v[60:61], v[56:59], off offset:1024
	s_waitcnt vmcnt(5)
	v_and_b32_e32 v184, 0xffff0000, v44
	v_lshlrev_b32_e32 v182, 16, v44
	v_mul_f32_e32 v44, 0xbfb8aa3b, v184
	v_exp_f32_e32 v44, v44
	v_mov_b32_e32 v142, v161
	v_pk_mul_f32 v[160:161], v[104:105], v[142:143]
	v_lshlrev_b32_e32 v183, 16, v40
	v_and_b32_e32 v185, 0xffff0000, v40
	v_add_f32_e32 v40, 1.0, v44
	v_lshlrev_b32_e32 v188, 16, v45
	v_add_f32_e32 v161, v160, v161
	v_rcp_f32_e32 v160, v40
	v_mul_f32_e32 v40, 0xbfb8aa3b, v188
	v_exp_f32_e32 v44, v40
	v_and_b32_e32 v40, 0xffff0000, v45
	v_mul_f32_e32 v45, 0xbfb8aa3b, v40
	v_lshlrev_b32_e32 v60, 16, v49
	v_and_b32_e32 v128, 0xffff0000, v49
	v_mul_f32_e32 v49, 0xbfb8aa3b, v182
	v_exp_f32_e32 v45, v45
	v_exp_f32_e32 v49, v49
	v_mov_b32_e32 v140, v159
	v_pk_mul_f32 v[166:167], v[98:99], v[140:141]
	v_mov_b32_e32 v138, v157
	v_add_f32_e32 v44, 1.0, v44
	v_mov_b32_e32 v144, v163
	v_add_f32_e32 v167, v166, v167
	v_pk_mul_f32 v[168:169], v[100:101], v[138:139]
	v_rcp_f32_e32 v166, v44
	v_add_f32_e32 v44, 1.0, v45
	v_pk_mul_f32 v[162:163], v[102:103], v[144:145]
	v_add_f32_e32 v169, v168, v169
	v_add_f32_e32 v49, 1.0, v49
	v_rcp_f32_e32 v168, v44
	v_lshlrev_b32_e32 v44, 16, v46
	v_and_b32_e32 v190, 0xffff0000, v46
	v_add_f32_e32 v163, v162, v163
	v_rcp_f32_e32 v162, v49
	v_mul_f32_e32 v49, 0xbfb8aa3b, v44
	v_mul_f32_e32 v46, 0xbfb8aa3b, v190
	v_exp_f32_e32 v49, v49
	v_exp_f32_e32 v46, v46
	v_mov_b32_e32 v136, v155
	v_mov_b32_e32 v134, v153
	v_pk_mul_f32 v[170:171], v[94:95], v[136:137]
	v_pk_mul_f32 v[172:173], v[96:97], v[134:135]
	v_lshlrev_b32_e32 v45, 16, v42
	v_add_f32_e32 v49, 1.0, v49
	v_and_b32_e32 v191, 0xffff0000, v42
	v_add_f32_e32 v42, 1.0, v46
	v_lshlrev_b32_e32 v192, 16, v47
	v_add_f32_e32 v171, v170, v171
	v_add_f32_e32 v173, v172, v173
	v_rcp_f32_e32 v170, v49
	v_rcp_f32_e32 v172, v42
	v_mul_f32_e32 v42, 0xbfb8aa3b, v192
	v_add_u32_e32 v49, 4, v124
	v_lshlrev_b32_e32 v56, 16, v48
	v_lshlrev_b32_e32 v58, 16, v52
	v_exp_f32_e32 v46, v42
	v_and_b32_e32 v42, 0xffff0000, v47
	v_cmp_gt_u32_e32 vcc, s46, v49
	s_waitcnt vmcnt(3)
	v_lshlrev_b32_e32 v59, 16, v36
	v_lshlrev_b32_e32 v57, 16, v32
	v_and_b32_e32 v48, 0xffff0000, v48
	v_and_b32_e32 v52, 0xffff0000, v52
	v_lshlrev_b32_e32 v62, 16, v53
	v_and_b32_e32 v146, 0xffff0000, v53
	v_mul_f32_e32 v47, 0xbfb8aa3b, v42
	v_cndmask_b32_e64 v67, 0, 1.0, vcc
	v_and_b32_e32 v53, 0xffff0000, v36
	v_and_b32_e32 v49, 0xffff0000, v32
	v_lshlrev_b32_e32 v61, 16, v33
	v_and_b32_e32 v129, 0xffff0000, v33
	v_pk_mul_f32 v[32:33], v[56:57], v[58:59]
	v_exp_f32_e32 v47, v47
	v_lshlrev_b32_e32 v63, 16, v37
	v_and_b32_e32 v147, 0xffff0000, v37
	v_pk_mul_f32 v[32:33], v[66:67], v[32:33]
	v_pk_mul_f32 v[36:37], v[48:49], v[52:53]
	v_fmac_f32_e32 v163, v12, v32
	v_pk_mul_f32 v[36:37], v[66:67], v[36:37]
	v_pk_mul_f32 v[48:49], v[60:61], v[62:63]
	v_lshlrev_b32_e32 v148, 16, v50
	v_lshlrev_b32_e32 v150, 16, v54
	v_lshlrev_b32_e32 v152, 16, v51
	v_and_b32_e32 v156, 0xffff0000, v51
	v_mov_b32_e32 v132, v151
	v_mov_b32_e32 v130, v149
	v_lshlrev_b32_e32 v151, 16, v38
	v_lshlrev_b32_e32 v149, 16, v34
	v_and_b32_e32 v51, 0xffff0000, v34
	v_lshlrev_b32_e32 v153, 16, v35
	v_and_b32_e32 v157, 0xffff0000, v35
	v_pk_mul_f32 v[34:35], v[162:163], v[182:183]
	v_fmac_f32_e32 v161, v13, v36
	v_pk_mul_f32 v[48:49], v[66:67], v[48:49]
	v_pk_mul_f32 v[56:57], v[128:129], v[146:147]
	v_and_b32_e32 v50, 0xffff0000, v50
	v_and_b32_e32 v54, 0xffff0000, v54
	v_lshlrev_b32_e32 v154, 16, v55
	v_and_b32_e32 v158, 0xffff0000, v55
	v_pk_mul_f32 v[174:175], v[90:91], v[132:133]
	v_lshlrev_b32_e32 v189, 16, v41
	v_add_f32_e32 v46, 1.0, v46
	v_and_b32_e32 v55, 0xffff0000, v38
	v_lshlrev_b32_e32 v155, 16, v39
	v_and_b32_e32 v159, 0xffff0000, v39
	v_pk_mul_f32 v[38:39], v[160:161], v[184:185]
	v_fmac_f32_e32 v167, v14, v48
	v_pk_mul_f32 v[56:57], v[66:67], v[56:57]
	v_pk_mul_f32 v[58:59], v[148:149], v[150:151]
	v_mul_f32_e32 v64, v35, v35
	v_add_f32_e32 v175, v174, v175
	v_pk_mul_f32 v[180:181], v[92:93], v[130:131]
	v_and_b32_e32 v41, 0xffff0000, v41
	v_rcp_f32_e32 v174, v46
	v_add_f32_e32 v46, 1.0, v47
	v_pk_mul_f32 v[52:53], v[166:167], v[188:189]
	v_fmac_f32_e32 v169, v15, v56
	v_pk_mul_f32 v[58:59], v[66:67], v[58:59]
	v_pk_mul_f32 v[50:51], v[50:51], v[54:55]
	v_fmac_f32_e32 v64, v39, v39
	v_add_f32_e32 v181, v180, v181
	v_rcp_f32_e32 v180, v46
	v_pk_mul_f32 v[40:41], v[168:169], v[40:41]
	v_fmac_f32_e32 v171, v4, v58
	v_pk_mul_f32 v[50:51], v[66:67], v[50:51]
	v_pk_mul_f32 v[60:61], v[152:153], v[154:155]
	v_fmac_f32_e32 v64, v53, v53
	v_pk_mul_f32 v[44:45], v[170:171], v[44:45]
	v_fmac_f32_e32 v173, v5, v50
	v_pk_mul_f32 v[60:61], v[66:67], v[60:61]
	v_pk_mul_f32 v[124:125], v[156:157], v[158:159]
	v_fmac_f32_e32 v64, v41, v41
	v_lshlrev_b32_e32 v193, 16, v43
	v_pk_mul_f32 v[54:55], v[172:173], v[190:191]
	v_fmac_f32_e32 v175, v6, v60
	v_pk_mul_f32 v[124:125], v[66:67], v[124:125]
	v_fmac_f32_e32 v64, v45, v45
	v_and_b32_e32 v43, 0xffff0000, v43
	v_pk_mul_f32 v[62:63], v[174:175], v[192:193]
	v_fmac_f32_e32 v181, v7, v124
	v_fmac_f32_e32 v64, v55, v55
	v_pk_mul_f32 v[42:43], v[180:181], v[42:43]
	v_fmac_f32_e32 v64, v63, v63
	v_fmac_f32_e32 v64, v43, v43
	v_pk_mul_f32 v[32:33], v[118:119], v[32:33]
	v_ashrrev_i32_e32 v127, 31, v126
	v_fma_f32 v32, v8, v145, v32
	v_lshl_add_u64 v[46:47], s[38:39], 0, v[126:127]
	v_add_f32_dpp v64, v64, v64 quad_perm:[1,0,3,2] row_mask:0xf bank_mask:0xf
	v_add_f32_e32 v127, v32, v33
	v_pk_mul_f32 v[32:33], v[120:121], v[36:37]
	v_lshlrev_b64 v[46:47], 11, v[46:47]
	v_fma_f32 v32, v9, v143, v32
	v_add_f32_dpp v36, v64, v64 quad_perm:[2,3,0,1] row_mask:0xf bank_mask:0xf
	v_add_f32_e32 v37, v32, v33
	v_pk_mul_f32 v[32:33], v[114:115], v[48:49]
	v_lshl_add_u64 v[46:47], v[72:73], 0, v[46:47]
	v_fma_f32 v32, v10, v141, v32
	v_add_f32_dpp v36, v36, v36 row_half_mirror row_mask:0xf bank_mask:0xf
	v_add_f32_e32 v49, v32, v33
	v_pk_mul_f32 v[32:33], v[116:117], v[56:57]
	v_add_f32_dpp v36, v36, v36 row_mirror row_mask:0xf bank_mask:0xf
	v_fma_f32 v32, v11, v139, v32
	ds_swizzle_b32 v48, v36 offset:swizzle(SWAP,16)
	v_add_f32_e32 v57, v32, v33
	v_pk_mul_f32 v[32:33], v[110:111], v[58:59]
	s_nop 0
	v_fma_f32 v32, v0, v137, v32
	v_add_f32_e32 v59, v32, v33
	v_pk_mul_f32 v[32:33], v[112:113], v[50:51]
	s_nop 0
	v_fma_f32 v32, v1, v135, v32
	v_add_f32_e32 v51, v32, v33
	s_waitcnt lgkmcnt(0)
	v_add_f32_e32 v32, v36, v48
	v_mov_b32_e32 v33, v32
	s_nop 1
	v_permlane32_swap_b32_e32 v32, v33
	v_add_f32_e32 v32, v32, v33
	v_fmamk_f32 v32, v32, 0x3b000000, v196
	v_mul_f32_e32 v33, 0x4b800000, v32
	v_cmp_gt_f32_e32 vcc, s35, v32
	s_nop 1
	v_cndmask_b32_e32 v32, v32, v33, vcc
	v_rsq_f32_e32 v36, v32
	v_pk_mul_f32 v[32:33], v[106:107], v[60:61]
	s_nop 0
	v_fma_f32 v32, v2, v133, v32
	v_add_f32_e32 v61, v32, v33
	v_mul_f32_e32 v32, 0x45800000, v36
	v_cndmask_b32_e32 v36, v36, v32, vcc
	v_mul_f32_e32 v32, v35, v36
	v_mul_f32_e32 v33, v39, v36
	v_mul_f32_e32 v32, v34, v32
	v_mul_f32_e32 v33, v38, v33
	v_cvt_pk_bf16_f32 v32, v32, v33
	v_mul_f32_e32 v33, v53, v36
	v_mul_f32_e32 v34, v41, v36
	v_mul_f32_e32 v33, v52, v33
	v_mul_f32_e32 v34, v40, v34
	v_cvt_pk_bf16_f32 v33, v33, v34
	v_mul_f32_e32 v34, v45, v36
	v_mul_f32_e32 v35, v55, v36
	v_mul_f32_e32 v34, v44, v34
	v_mul_f32_e32 v35, v54, v35
	v_cvt_pk_bf16_f32 v34, v34, v35
	v_mul_f32_e32 v35, v63, v36
	v_mul_f32_e32 v35, v62, v35
	v_mul_f32_e32 v36, v43, v36
	v_mul_f32_e32 v36, v42, v36
	v_cvt_pk_bf16_f32 v35, v35, v36
	global_store_dwordx4 v[46:47], v[32:35], off offset:1024
	s_nop 1
	v_pk_mul_f32 v[32:33], v[108:109], v[124:125]
	v_ashrrev_i32_e32 v123, 31, v122
	v_fma_f32 v35, v3, v131, v32
	s_waitcnt vmcnt(3)
	v_lshlrev_b32_e32 v32, 16, v28
	v_mul_f32_e32 v34, 0xbfb8aa3b, v32
	v_exp_f32_e32 v36, v34
	v_and_b32_e32 v34, 0xffff0000, v28
	v_mul_f32_e32 v28, 0xbfb8aa3b, v34
	v_exp_f32_e32 v28, v28
	v_add_f32_e32 v39, v35, v33
	v_add_f32_e32 v33, 1.0, v36
	v_rcp_f32_e32 v126, v33
	v_add_f32_e32 v28, 1.0, v28
	v_rcp_f32_e32 v36, v28
	v_lshlrev_b32_e32 v28, 16, v29
	v_lshlrev_b32_e32 v33, 16, v24
	v_and_b32_e32 v35, 0xffff0000, v24
	v_mul_f32_e32 v24, 0xbfb8aa3b, v28
	v_pk_mul_f32 v[34:35], v[36:37], v[34:35]
	v_exp_f32_e32 v36, v24
	v_and_b32_e32 v24, 0xffff0000, v29
	v_mul_f32_e32 v29, 0xbfb8aa3b, v24
	v_exp_f32_e32 v37, v29
	v_add_f32_e32 v36, 1.0, v36
	v_rcp_f32_e32 v48, v36
	v_lshlrev_b32_e32 v29, 16, v25
	v_add_f32_e32 v36, 1.0, v37
	v_rcp_f32_e32 v56, v36
	v_lshlrev_b32_e32 v36, 16, v30
	v_mul_f32_e32 v37, 0xbfb8aa3b, v36
	v_exp_f32_e32 v37, v37
	v_and_b32_e32 v25, 0xffff0000, v25
	v_pk_mul_f32 v[40:41], v[56:57], v[24:25]
	v_pk_mul_f32 v[32:33], v[126:127], v[32:33]
	v_add_f32_e32 v24, 1.0, v37
	v_rcp_f32_e32 v58, v24
	v_and_b32_e32 v24, 0xffff0000, v30
	v_mul_f32_e32 v25, 0xbfb8aa3b, v24
	v_exp_f32_e32 v30, v25
	v_lshlrev_b32_e32 v37, 16, v26
	v_and_b32_e32 v25, 0xffff0000, v26
	v_pk_mul_f32 v[28:29], v[48:49], v[28:29]
	v_add_f32_e32 v26, 1.0, v30
	v_lshlrev_b32_e32 v30, 16, v31
	v_rcp_f32_e32 v50, v26
	v_mul_f32_e32 v26, 0xbfb8aa3b, v30
	v_exp_f32_e32 v38, v26
	v_and_b32_e32 v26, 0xffff0000, v31
	v_mul_f32_e32 v31, 0xbfb8aa3b, v26
	v_exp_f32_e32 v31, v31
	v_pk_mul_f32 v[42:43], v[50:51], v[24:25]
	v_add_f32_e32 v24, 1.0, v38
	v_rcp_f32_e32 v60, v24
	v_add_f32_e32 v24, 1.0, v31
	v_rcp_f32_e32 v38, v24
	v_mul_f32_e32 v24, v33, v33
	v_fmac_f32_e32 v24, v35, v35
	v_fmac_f32_e32 v24, v29, v29
	v_pk_mul_f32 v[36:37], v[58:59], v[36:37]
	v_fmac_f32_e32 v24, v41, v41
	v_lshlrev_b32_e32 v31, 16, v27
	v_fmac_f32_e32 v24, v37, v37
	v_pk_mul_f32 v[30:31], v[60:61], v[30:31]
	v_and_b32_e32 v27, 0xffff0000, v27
	v_fmac_f32_e32 v24, v43, v43
	v_pk_mul_f32 v[38:39], v[38:39], v[26:27]
	v_fmac_f32_e32 v24, v31, v31
	v_fmac_f32_e32 v24, v39, v39
	s_nop 1
	v_add_f32_dpp v24, v24, v24 quad_perm:[1,0,3,2] row_mask:0xf bank_mask:0xf
	s_nop 1
	v_add_f32_dpp v24, v24, v24 quad_perm:[2,3,0,1] row_mask:0xf bank_mask:0xf
	s_nop 1
	v_add_f32_dpp v24, v24, v24 row_half_mirror row_mask:0xf bank_mask:0xf
	s_nop 1
	v_add_f32_dpp v24, v24, v24 row_mirror row_mask:0xf bank_mask:0xf
	v_mov_b32_e32 v25, v24
	s_nop 1
	v_permlane16_swap_b32_e32 v24, v25
	v_add_f32_e32 v24, v24, v25
	v_mov_b32_e32 v25, v24
	s_nop 1
	v_permlane32_swap_b32_e32 v24, v25
	v_add_f32_e32 v24, v24, v25
	v_fmamk_f32 v24, v24, 0x3b000000, v196
	v_mul_f32_e32 v25, 0x4b800000, v24
	v_cmp_gt_f32_e32 vcc, s35, v24
	s_nop 1
	v_cndmask_b32_e32 v24, v24, v25, vcc
	v_rsq_f32_e32 v24, v24
	s_nop 0
	v_mul_f32_e32 v25, 0x45800000, v24
	v_cndmask_b32_e32 v27, v24, v25, vcc
	v_mul_f32_e32 v24, v33, v27
	v_mul_f32_e32 v25, v35, v27
	v_mul_f32_e32 v24, v32, v24
	v_mul_f32_e32 v25, v34, v25
	v_cvt_pk_bf16_f32 v24, v24, v25
	v_mul_f32_e32 v25, v29, v27
	v_mul_f32_e32 v26, v41, v27
	v_mul_f32_e32 v25, v28, v25
	v_mul_f32_e32 v26, v40, v26
	v_cvt_pk_bf16_f32 v25, v25, v26
	v_mul_f32_e32 v26, v37, v27
	v_mul_f32_e32 v28, v43, v27
	v_mul_f32_e32 v26, v36, v26
	v_mul_f32_e32 v28, v42, v28
	v_cvt_pk_bf16_f32 v26, v26, v28
	v_mul_f32_e32 v28, v31, v27
	v_mul_f32_e32 v27, v39, v27
	v_mul_f32_e32 v28, v30, v28
	v_mul_f32_e32 v27, v38, v27
	v_cvt_pk_bf16_f32 v27, v28, v27
	v_lshl_add_u64 v[28:29], s[38:39], 0, v[122:123]
	v_lshlrev_b64 v[28:29], 11, v[28:29]
	v_lshl_add_u64 v[28:29], v[72:73], 0, v[28:29]
	global_store_dwordx4 v[28:29], v[24:27], off offset:1024
	s_and_b64 vcc, exec, s[0:1]
	s_mov_b64 s[0:1], 0
	s_cbranch_vccnz .LBB0_270
	s_bitcmp1_b32 s3, 3
	s_cbranch_scc0 .Lb_adv
	s_mov_b32 s98, 1
	s_branch .LBB0_255
